# first-tile rsqrt cache fill: ss loads issued at the top of the phase prologue (first tile's row panel from blockIdx), reduction in the stage-load wait
# speedup vs baseline: 1.0058x; 1.0058x over previous
.LBB0_131:
	s_mov_b32 s52, -1
	v_writelane_b32 v248, s52, 41
	s_lshl_b32 s36, s11, 6
	v_mov_b32_e32 v9, v199
	v_readlane_b32 s1, v251, 0
	s_cmp_ge_i32 s1, s36
	v_readfirstlane_b32 s19, v9
	s_mov_b32 s55, s44
	s_cbranch_scc1 .LBB0_151
	s_and_b32 s22, s1, 7
	s_bfe_u32 s23, s1, 0x30003
	s_lshl_b32 s22, s22, 3
	s_or_b32 s22, s22, s23
	v_writelane_b32 v248, s22, 41
	v_and_b32_e32 v174, 15, v199
	v_lshrrev_b32_e32 v175, 8, v199
	v_lshl_or_b32 v174, v175, 6, v174
	v_lshl_add_u32 v174, s22, 8, v174
	v_readlane_b32 s22, v249, 56
	v_bfe_u32 v176, v199, 4, 2
	v_readlane_b32 s23, v249, 57
	v_lshlrev_b32_e32 v176, 4, v176
	v_mov_b32_e32 v177, 0
	s_nop 0
	v_lshl_add_u64 v[178:179], s[22:23], 0, v[176:177]
	s_bfe_u32 s22, s19, 0x20006
	s_and_b32 s23, s22, 1
	s_lshl_b32 s23, s23, 5
	s_lshr_b32 s22, s22, 1
	s_lshl_b32 s22, s22, 7
	s_add_i32 s22, s22, s23
	v_add_u32_e32 v176, s22, v174
	v_lshlrev_b32_e32 v176, 6, v176
	v_lshl_add_u64 v[180:181], v[178:179], 0, v[176:177]
	global_load_dwordx4 v[128:131], v[180:181], off
	global_load_dwordx4 v[132:135], v[180:181], off offset:1024
	v_lshlrev_b32_e32 v0, 4, v9
	s_waitcnt lgkmcnt(0)
	v_add_u32_e32 v1, 0x2000, v0
	v_ashrrev_i32_e32 v2, 31, v1
	v_lshrrev_b32_e32 v2, 22, v2
	v_add_u32_e32 v2, v1, v2
	v_ashrrev_i32_e32 v8, 10, v2
	v_mul_i32_i24_e32 v2, 0x400, v8
	v_sub_u32_e32 v1, v1, v2
	v_lshrrev_b32_e32 v2, 4, v1
	v_bitop3_b32 v1, v2, v1, 32 bitop3:0x6c
	v_ashrrev_i32_e32 v2, 31, v1
	v_lshrrev_b32_e32 v2, 26, v2
	v_add_u32_e32 v2, v1, v2
	v_lshlrev_b32_e32 v3, 3, v8
	v_ashrrev_i32_e32 v10, 6, v2
	v_and_b32_e32 v3, -16, v3
	v_add_u32_e32 v3, v10, v3
	v_and_b32_e32 v4, 3, v10
	s_mov_b32 s2, 0x1fffe0
	v_lshrrev_b32_e32 v5, 2, v3
	v_lshlrev_b32_e32 v6, 1, v3
	v_and_b32_e32 v2, 0xc0, v2
	v_and_or_b32 v4, v3, s2, v4
	v_and_b32_e32 v5, 4, v5
	v_and_b32_e32 v6, 24, v6
	v_sub_u32_e32 v1, v1, v2
	v_or3_b32 v4, v4, v5, v6
	v_lshlrev_b32_e32 v5, 5, v8
	v_ashrrev_i16_sdwa v1, v223, sext(v1) dst_sel:DWORD dst_unused:UNUSED_PAD src0_sel:DWORD src1_sel:BYTE_0
	v_and_b32_e32 v5, 32, v5
	v_bfe_i32 v11, v1, 0, 16
	v_add_lshl_u32 v1, v5, v11, 1
	s_waitcnt vmcnt(2)
	v_lshl_add_u32 v152, v4, 11, v1
	v_lshl_add_u32 v154, v3, 11, v1
	v_bfe_i32 v1, v9, 27, 1
	v_lshrrev_b32_e32 v1, 22, v1
	v_add_u32_e32 v1, v0, v1
	v_and_b32_e32 v1, 0xfffffc00, v1
	v_sub_u32_e32 v0, v0, v1
	v_lshrrev_b32_e32 v1, 4, v0
	v_ashrrev_i32_e32 v2, 31, v9
	v_bitop3_b32 v0, v1, v0, 32 bitop3:0x6c
	v_lshrrev_b32_e32 v2, 26, v2
	v_ashrrev_i32_e32 v1, 31, v0
	v_add_u32_e32 v2, v9, v2
	v_lshrrev_b32_e32 v1, 26, v1
	v_ashrrev_i32_e32 v13, 6, v2
	v_add_u32_e32 v1, v0, v1
	v_lshlrev_b32_e32 v2, 3, v13
	v_ashrrev_i32_e32 v12, 6, v1
	v_and_b32_e32 v2, -16, v2
	v_add_u32_e32 v2, v12, v2
	v_and_b32_e32 v3, 3, v12
	s_ashr_i32 s21, s19, 6
	v_and_or_b32 v3, v2, s2, v3
	s_lshl_b32 s2, s11, 3
	v_readlane_b32 s12, v250, 5
	s_ashr_i32 s20, s19, 8
	s_lshl_b32 s1, s21, 10
	s_or_b32 s3, s2, 1
	v_readlane_b32 s13, v250, 6
	s_and_b64 s[12:13], s[12:13], exec
	v_and_b32_e32 v1, 0xc0, v1
	s_cselect_b32 s12, s3, s2
	s_lshl_b32 s9, s11, 2
	v_sub_u32_e32 v0, v0, v1
	v_cvt_f32_u32_e32 v1, s9
	v_lshrrev_b32_e32 v4, 2, v2
	v_lshlrev_b32_e32 v5, 1, v2
	v_and_b32_e32 v4, 4, v4
	v_and_b32_e32 v5, 24, v5
	v_rcp_iflag_f32_e32 v1, v1
	v_or3_b32 v3, v3, v4, v5
	v_lshlrev_b32_e32 v4, 5, v13
	v_ashrrev_i16_sdwa v0, v223, sext(v0) dst_sel:DWORD dst_unused:UNUSED_PAD src0_sel:DWORD src1_sel:BYTE_0
	v_and_b32_e32 v4, 32, v4
	v_bfe_i32 v14, v0, 0, 16
	v_add_lshl_u32 v0, v4, v14, 1
	v_lshl_add_u32 v196, v3, 11, v0
	v_lshl_add_u32 v156, v2, 11, v0
	v_mul_f32_e32 v0, 0x4f7ffffe, v1
	v_cvt_u32_f32_e32 v0, v0
	v_readlane_b32 s11, v250, 12
	s_mul_i32 s11, s12, s11
	v_readlane_b32 s12, v250, 7
	s_add_i32 s12, s11, s12
	s_sub_i32 s11, 0, s9
	v_readfirstlane_b32 s15, v0
	s_mul_i32 s11, s11, s15
	s_mul_hi_u32 s11, s15, s11
	s_abs_i32 s14, s12
	s_add_i32 s11, s15, s11
	s_mul_hi_u32 s15, s14, s11
	s_mul_i32 s17, s15, s9
	s_sub_i32 s14, s14, s17
	s_ashr_i32 s13, s12, 31
	s_add_i32 s17, s15, 1
	s_sub_i32 s18, s14, s9
	s_cmp_ge_u32 s14, s9
	s_cselect_b32 s15, s17, s15
	s_cselect_b32 s14, s18, s14
	s_add_i32 s17, s15, 1
	s_cmp_ge_u32 s14, s9
	s_cselect_b32 s14, s17, s15
	s_xor_b32 s14, s14, s13
	s_sub_i32 s13, s14, s13
	s_mul_i32 s14, s13, s9
	s_sub_i32 s22, s12, s14
	s_and_b32 s14, s13, 1
	s_mul_i32 s14, s14, s9
	s_add_i32 s22, s22, s14
	s_lshr_b32 s14, s13, 1
	s_lshl_b32 s14, s14, 3
	s_lshr_b32 s18, s22, 3
	s_and_b32 s12, s22, 7
	s_add_i32 s34, s14, s12
	s_ashr_i32 s35, s34, 31
	s_bfe_i64 s[14:15], s[18:19], 0x100000
	s_lshl_b64 s[12:13], s[34:35], 19
	s_lshl_b64 s[14:15], s[14:15], 19
	s_add_u32 s44, s6, s14
	s_addc_u32 s45, s7, s15
	s_add_i32 s14, s1, 0
	s_add_i32 m0, s14, 0x10000
	v_mov_b32_e32 v153, v197
	global_load_lds_dwordx4 v196, s[44:45]
	s_add_i32 m0, s14, 0x12000
	s_add_u32 s22, s44, 0x40000
	global_load_lds_dwordx4 v152, s[44:45]
	s_addc_u32 s23, s45, 0
	s_add_i32 m0, s14, 0x14000
	v_mov_b32_e32 v157, v197
	global_load_lds_dwordx4 v196, s[22:23]
	s_add_i32 m0, s14, 0x16000
	s_add_u32 s40, s80, s12
	s_addc_u32 s41, s81, s13
	s_add_i32 s15, s14, 0x2000
	global_load_lds_dwordx4 v152, s[22:23]
	s_mov_b32 m0, s14
	s_add_u32 s12, s40, 0x40000
	global_load_lds_dwordx4 v156, s[40:41]
	s_mov_b32 m0, s15
	s_addc_u32 s13, s41, 0
	s_add_i32 s17, s14, 0x4000
	global_load_lds_dwordx4 v154, s[40:41]
	s_mov_b32 m0, s17
	s_add_i32 s26, s14, 0x6000
	global_load_lds_dwordx4 v156, s[12:13]
	s_mov_b32 m0, s26
	v_mov_b32_e32 v155, v197
	global_load_lds_dwordx4 v154, s[12:13]
	s_cmp_eq_u32 s20, 1
	s_mov_b32 s56, s30
	v_lshl_add_u64 v[6:7], s[44:45], 0, v[196:197]
	v_lshl_add_u64 v[4:5], s[44:45], 0, v[152:153]
	v_lshl_add_u64 v[0:1], s[40:41], 0, v[156:157]
	s_cselect_b64 s[12:13], -1, 0
	s_cmp_lg_u32 s20, 1
	v_lshl_add_u64 v[2:3], s[40:41], 0, v[154:155]
	s_cbranch_scc1 .LBB0_134
	s_barrier
.LBB0_134:
	s_lshl_b32 s21, s21, 5
	s_and_b32 s21, s21, 0x60
	s_add_i32 m0, s14, 0x18000
	v_lshl_add_u64 v[6:7], v[6:7], 0, s[88:89]
	s_lshl_b32 s24, s20, 13
	s_lshl_b32 s25, s21, 7
	s_waitcnt vmcnt(8)
	v_mov_b32_e32 v212, 0x358637bd
	v_add_f32_e32 v128, v129, v128
	v_add_f32_e32 v130, v130, v131
	v_add_f32_e32 v204, v128, v130
	v_add_f32_e32 v132, v133, v132
	v_add_f32_e32 v134, v134, v135
	v_add_f32_e32 v205, v132, v134
	v_mov_b32_e32 v180, v204
	s_nop 1
	v_permlane16_swap_b32_e32 v204, v180
	v_add_f32_e32 v204, v204, v180
	v_mov_b32_e32 v180, v204
	s_nop 1
	v_permlane32_swap_b32_e32 v204, v180
	v_add_f32_e32 v204, v204, v180
	v_mov_b32_e32 v180, v205
	s_nop 1
	v_permlane16_swap_b32_e32 v205, v180
	v_add_f32_e32 v205, v205, v180
	v_mov_b32_e32 v180, v205
	s_nop 1
	v_permlane32_swap_b32_e32 v205, v180
	v_add_f32_e32 v205, v205, v180
	v_fmamk_f32 v204, v204, 0x3a800000, v212
	v_mul_f32_e32 v180, 0x4b800000, v204
	v_cmp_gt_f32_e32 vcc, s39, v204
	s_nop 1
	v_cndmask_b32_e32 v204, v204, v180, vcc
	v_rsq_f32_e32 v204, v204
	s_nop 0
	v_mul_f32_e32 v180, 0x45800000, v204
	v_cndmask_b32_e32 v204, v204, v180, vcc
	v_fmamk_f32 v205, v205, 0x3a800000, v212
	v_mul_f32_e32 v180, 0x4b800000, v205
	v_cmp_gt_f32_e32 vcc, s39, v205
	s_nop 1
	v_cndmask_b32_e32 v205, v205, v180, vcc
	v_rsq_f32_e32 v205, v205
	s_nop 0
	v_mul_f32_e32 v180, 0x45800000, v205
	v_cndmask_b32_e32 v205, v205, v180, vcc
	v_lshrrev_b32_e32 v180, 8, v199
	v_and_b32_e32 v181, 15, v199
	v_lshlrev_b32_e32 v180, 11, v180
	v_lshl_add_u32 v181, v181, 2, v180
	s_bfe_u32 s22, s19, 0x20006
	s_lshl_b32 s22, s22, 7
	s_add_i32 s22, s22, 0x20040
	v_add_u32_e32 v181, s22, v181
	ds_write_b32 v181, v204
	ds_write_b32 v181, v205 offset:64
	ds_write_b32 v181, v204 offset:512
	ds_write_b32 v181, v205 offset:576
	ds_write_b32 v181, v204 offset:1024
	ds_write_b32 v181, v205 offset:1088
	ds_write_b32 v181, v204 offset:1536
	ds_write_b32 v181, v205 offset:1600
	s_waitcnt vmcnt(2)
	s_barrier
	global_load_lds_dwordx4 v[6:7], off
	v_lshl_add_u64 v[4:5], v[4:5], 0, s[88:89]
	s_add_i32 m0, s14, 0x1a000
	s_add_i32 s27, s14, 0x8000
	s_add_i32 s28, s14, 0xa000
	global_load_lds_dwordx4 v[4:5], off
	v_lshl_add_u64 v[0:1], v[0:1], 0, s[88:89]
	s_mov_b32 m0, s27
	s_add_u32 s22, s44, 0x40080
	global_load_lds_dwordx4 v[0:1], off
	v_lshl_add_u64 v[0:1], v[2:3], 0, s[88:89]
	s_mov_b32 m0, s28
	s_addc_u32 s23, s45, 0
	global_load_lds_dwordx4 v[0:1], off
	s_add_i32 m0, s14, 0x1c000
	v_lshl_add_u64 v[0:1], s[22:23], 0, v[196:197]
	global_load_lds_dwordx4 v[0:1], off
	v_lshl_add_u64 v[0:1], s[22:23], 0, v[152:153]
	s_add_i32 m0, s14, 0x1e000
	v_bfe_u32 v2, v9, 4, 2
	global_load_lds_dwordx4 v[0:1], off
	v_and_b32_e32 v1, 15, v9
	v_lshlrev_b32_e32 v0, 4, v2
	v_lshlrev_b32_e32 v3, 2, v9
	v_lshl_or_b32 v184, s20, 6, v1
	v_lshl_or_b32 v1, v1, 6, v0
	v_and_b32_e32 v3, 32, v3
	v_readlane_b32 s22, v249, 56
	v_bitop3_b32 v4, v1, s24, v3 bitop3:0xde
	v_bitop3_b32 v185, v1, s25, v3 bitop3:0xde
	v_mov_b32_e32 v1, v197
	v_readlane_b32 s23, v249, 57
	s_cmpk_lt_u32 s19, 0x100
	s_sext_i32_i16 s33, s18
	v_lshl_add_u64 v[158:159], s[22:23], 0, v[0:1]
	v_lshlrev_b32_e32 v0, 14, v13
	v_and_b32_e32 v0, 0xffff8000, v0
	v_lshl_add_u32 v0, v12, 11, v0
	v_and_b32_e32 v1, 1, v13
	v_lshl_or_b32 v0, v1, 6, v0
	v_lshl_add_u32 v160, v14, 1, v0
	v_lshlrev_b32_e32 v0, 14, v8
	v_and_b32_e32 v0, 0xffff8000, v0
	v_lshl_add_u32 v0, v10, 11, v0
	v_and_b32_e32 v1, 1, v8
	v_lshl_or_b32 v0, v1, 6, v0
	s_cselect_b64 s[18:19], -1, 0
	v_lshl_or_b32 v186, v2, 3, s21
	v_mov_b32_e32 v161, v197
	v_lshl_add_u32 v162, v11, 1, v0
	v_mov_b32_e32 v163, v197
	s_mov_b32 s29, 0
	v_add_u32_e32 v187, 0, v4
	v_mov_b64_e32 v[164:165], s[36:37]
	s_branch .LBB0_137
